# out0/out1 epilogue pass 1: prefetch depth 5/6 blocks using additional free VGPRs
# speedup vs baseline: 1.0593x; 1.0593x over previous
.LBB0_390:
	s_lshl_b32 s34, s15, 8
	v_mov_b32 v128, 0
	s_add_i32 s82, s57, s34
	v_lshlrev_b32_e32 v154, 3, v132
	v_or_b32_e32 v128, s2, v154
	s_ashr_i32 s2, s82, 13
	s_mul_i32 s34, s2, 0xc00
	s_ashr_i32 s35, s34, 31
	s_ashr_i32 s83, s82, 31
	s_lshl_b64 s[34:35], s[34:35], 2
	v_or_b32_e32 v136, s58, v128
	s_add_u32 s58, s28, s34
	v_or_b32_e32 v140, s82, v152
	s_addc_u32 s59, s29, s35
	v_ashrrev_i32_e32 v141, 31, v140
	v_lshl_add_u64 v[128:129], v[136:137], 2, s[58:59]
	v_lshlrev_b64 v[130:131], 10, v[140:141]
	s_movk_i32 s2, 0x2000
	v_lshl_add_u64 v[130:131], v[130:131], 0, v[136:137]
	v_add_co_u32_e32 v146, vcc, s2, v128
	v_lshlrev_b64 v[148:149], 2, v[130:131]
	s_nop 0
	v_addc_co_u32_e32 v147, vcc, 0, v129, vcc
	v_lshl_add_u64 v[142:143], v[128:129], 0, s[6:7]
	v_lshl_add_u64 v[138:139], s[36:37], 0, v[148:149]
	global_load_dwordx4 v[212:215], v[146:147], off
	global_load_dwordx4 v[216:219], v[138:139], off offset:16
	global_load_dwordx4 v[220:223], v[138:139], off
	global_load_dwordx4 v[224:227], v[142:143], off offset:16
	global_load_dwordx4 v[228:231], v[142:143], off offset:80
	global_load_dwordx4 v[232:235], v[142:143], off offset:64
	global_load_dwordx4 v[238:241], v[138:139], off offset:64
	global_load_dwordx4 v[242:245], v[138:139], off offset:80
	global_load_dwordx4 v[246:249], v[142:143], off offset:144
	global_load_dwordx4 v[250:253], v[142:143], off offset:128
	global_load_dwordx4 v[162:165], v[138:139], off offset:128
	global_load_dwordx4 v[166:169], v[138:139], off offset:144
	global_load_dwordx4 v[172:175], v[142:143], off offset:208
	global_load_dwordx4 v[176:179], v[142:143], off offset:192
	global_load_dwordx4 v[180:183], v[138:139], off offset:192
	global_load_dwordx4 v[184:187], v[138:139], off offset:208
	global_load_dwordx4 v[188:191], v[142:143], off offset:272
	global_load_dwordx4 v[192:195], v[142:143], off offset:256
	global_load_dwordx4 v[196:199], v[138:139], off offset:256
	global_load_dwordx4 v[200:203], v[138:139], off offset:272
	v_readlane_b32 s48, v237, 1
	v_readlane_b32 s62, v237, 15
	v_readlane_b32 s63, v237, 16
	v_readlane_b32 s56, v237, 9
	v_readlane_b32 s57, v237, 10
	v_lshl_add_u64 v[148:149], s[62:63], 0, v[148:149]
	v_cmp_gt_u32_e32 vcc, 32, v153
	v_readlane_b32 s49, v237, 2
	v_readlane_b32 s50, v237, 3
	v_readlane_b32 s51, v237, 4
	v_readlane_b32 s52, v237, 5
	v_readlane_b32 s53, v237, 6
	v_readlane_b32 s54, v237, 7
	v_readlane_b32 s55, v237, 8
	v_readlane_b32 s58, v237, 11
	v_readlane_b32 s59, v237, 12
	v_readlane_b32 s60, v237, 13
	v_readlane_b32 s61, v237, 14
	s_waitcnt vmcnt(16)
	v_pk_fma_f32 v[128:129], v[112:113], v[212:213], v[220:221]
	v_pk_fma_f32 v[130:131], v[114:115], v[214:215], v[222:223]
	v_pk_fma_f32 v[132:133], v[120:121], v[224:225], v[216:217]
	v_pk_fma_f32 v[134:135], v[122:123], v[226:227], v[218:219]
	global_store_dwordx4 v[148:149], v[128:131], off
	global_store_dwordx4 v[148:149], v[132:135], off offset:16
	global_load_dwordx4 v[212:215], v[142:143], off offset:336
	global_load_dwordx4 v[216:219], v[142:143], off offset:320
	global_load_dwordx4 v[220:223], v[138:139], off offset:320
	global_load_dwordx4 v[224:227], v[138:139], off offset:336
	s_waitcnt vmcnt(18)
	v_pk_fma_f32 v[120:121], v[116:117], v[232:233], v[238:239]
	v_pk_fma_f32 v[124:125], v[124:125], v[228:229], v[242:243]
	v_pk_fma_f32 v[122:123], v[118:119], v[234:235], v[240:241]
	v_pk_fma_f32 v[126:127], v[126:127], v[230:231], v[244:245]
	global_store_dwordx4 v[148:149], v[120:123], off offset:64
	global_store_dwordx4 v[148:149], v[124:127], off offset:80
	global_load_dwordx4 v[228:231], v[142:143], off offset:400
	global_load_dwordx4 v[232:235], v[142:143], off offset:384
	global_load_dwordx4 v[238:241], v[138:139], off offset:384
	global_load_dwordx4 v[242:245], v[138:139], off offset:400
	s_waitcnt vmcnt(20)
	v_pk_fma_f32 v[112:113], v[96:97], v[250:251], v[162:163]
	v_pk_fma_f32 v[114:115], v[98:99], v[252:253], v[164:165]
	v_pk_fma_f32 v[116:117], v[104:105], v[246:247], v[166:167]
	v_pk_fma_f32 v[118:119], v[106:107], v[248:249], v[168:169]
	global_store_dwordx4 v[148:149], v[112:115], off offset:128
	global_store_dwordx4 v[148:149], v[116:119], off offset:144
	global_load_dwordx4 v[246:249], v[142:143], off offset:464
	global_load_dwordx4 v[250:253], v[142:143], off offset:448
	global_load_dwordx4 v[162:165], v[138:139], off offset:448
	global_load_dwordx4 v[166:169], v[138:139], off offset:464
	s_waitcnt vmcnt(22)
	v_pk_fma_f32 v[104:105], v[100:101], v[176:177], v[180:181]
	v_pk_fma_f32 v[108:109], v[108:109], v[172:173], v[184:185]
	v_pk_fma_f32 v[106:107], v[102:103], v[178:179], v[182:183]
	v_pk_fma_f32 v[110:111], v[110:111], v[174:175], v[186:187]
	global_store_dwordx4 v[148:149], v[104:107], off offset:192
	global_store_dwordx4 v[148:149], v[108:111], off offset:208
	s_waitcnt vmcnt(20)
	v_pk_fma_f32 v[96:97], v[80:81], v[192:193], v[196:197]
	v_pk_fma_f32 v[98:99], v[82:83], v[194:195], v[198:199]
	v_pk_fma_f32 v[100:101], v[88:89], v[188:189], v[200:201]
	v_pk_fma_f32 v[102:103], v[90:91], v[190:191], v[202:203]
	global_store_dwordx4 v[148:149], v[96:99], off offset:256
	global_store_dwordx4 v[148:149], v[100:103], off offset:272
	s_waitcnt vmcnt(16)
	v_pk_fma_f32 v[88:89], v[84:85], v[216:217], v[220:221]
	v_pk_fma_f32 v[92:93], v[92:93], v[212:213], v[224:225]
	v_pk_fma_f32 v[90:91], v[86:87], v[218:219], v[222:223]
	v_pk_fma_f32 v[94:95], v[94:95], v[214:215], v[226:227]
	global_store_dwordx4 v[148:149], v[88:91], off offset:320
	global_store_dwordx4 v[148:149], v[92:95], off offset:336
	s_waitcnt vmcnt(12)
	v_pk_fma_f32 v[80:81], v[64:65], v[232:233], v[238:239]
	v_pk_fma_f32 v[82:83], v[66:67], v[234:235], v[240:241]
	v_pk_fma_f32 v[84:85], v[72:73], v[228:229], v[242:243]
	v_pk_fma_f32 v[86:87], v[74:75], v[230:231], v[244:245]
	global_store_dwordx4 v[148:149], v[80:83], off offset:384
	global_store_dwordx4 v[148:149], v[84:87], off offset:400
	s_waitcnt vmcnt(8)
	v_pk_fma_f32 v[72:73], v[68:69], v[250:251], v[162:163]
	v_pk_fma_f32 v[76:77], v[76:77], v[246:247], v[166:167]
	v_pk_fma_f32 v[74:75], v[70:71], v[252:253], v[164:165]
	v_pk_fma_f32 v[78:79], v[78:79], v[248:249], v[168:169]
	global_store_dwordx4 v[148:149], v[72:75], off offset:448
	global_store_dwordx4 v[148:149], v[76:79], off offset:464
	v_or_b32_e32 v138, 32, v140
	v_ashrrev_i32_e32 v139, 31, v138
	v_lshlrev_b64 v[64:65], 10, v[138:139]
	v_lshl_add_u64 v[64:65], v[64:65], 0, v[136:137]
	v_lshlrev_b64 v[148:149], 2, v[64:65]
	v_lshl_add_u64 v[170:171], s[36:37], 0, v[148:149]
	global_load_dwordx4 v[172:175], v[170:171], off offset:16
	global_load_dwordx4 v[176:179], v[170:171], off
	global_load_dwordx4 v[180:183], v[146:147], off
	global_load_dwordx4 v[184:187], v[142:143], off offset:16
	global_load_dwordx4 v[188:191], v[142:143], off offset:80
	global_load_dwordx4 v[192:195], v[142:143], off offset:64
	global_load_dwordx4 v[196:199], v[170:171], off offset:64
	global_load_dwordx4 v[200:203], v[170:171], off offset:80
	global_load_dwordx4 v[212:215], v[142:143], off offset:144
	global_load_dwordx4 v[216:219], v[142:143], off offset:128
	global_load_dwordx4 v[220:223], v[170:171], off offset:128
	global_load_dwordx4 v[224:227], v[170:171], off offset:144
	global_load_dwordx4 v[228:231], v[142:143], off offset:208
	global_load_dwordx4 v[232:235], v[142:143], off offset:192
	global_load_dwordx4 v[238:241], v[170:171], off offset:192
	global_load_dwordx4 v[242:245], v[170:171], off offset:208
	global_load_dwordx4 v[246:249], v[142:143], off offset:272
	global_load_dwordx4 v[250:253], v[142:143], off offset:256
	global_load_dwordx4 v[162:165], v[170:171], off offset:256
	global_load_dwordx4 v[166:169], v[170:171], off offset:272
	v_lshl_add_u64 v[146:147], s[62:63], 0, v[148:149]
	s_waitcnt vmcnt(16)
	v_pk_fma_f32 v[64:65], v[48:49], v[180:181], v[176:177]
	v_pk_fma_f32 v[66:67], v[50:51], v[182:183], v[178:179]
	v_pk_fma_f32 v[68:69], v[56:57], v[184:185], v[172:173]
	v_pk_fma_f32 v[70:71], v[58:59], v[186:187], v[174:175]
	global_store_dwordx4 v[146:147], v[64:67], off
	global_store_dwordx4 v[146:147], v[68:71], off offset:16
	global_load_dwordx4 v[172:175], v[142:143], off offset:336
	global_load_dwordx4 v[176:179], v[142:143], off offset:320
	global_load_dwordx4 v[180:183], v[170:171], off offset:320
	global_load_dwordx4 v[184:187], v[170:171], off offset:336
	s_waitcnt vmcnt(18)
	v_pk_fma_f32 v[56:57], v[52:53], v[192:193], v[196:197]
	v_pk_fma_f32 v[60:61], v[60:61], v[188:189], v[200:201]
	v_pk_fma_f32 v[58:59], v[54:55], v[194:195], v[198:199]
	v_pk_fma_f32 v[62:63], v[62:63], v[190:191], v[202:203]
	global_store_dwordx4 v[146:147], v[56:59], off offset:64
	global_store_dwordx4 v[146:147], v[60:63], off offset:80
	global_load_dwordx4 v[188:191], v[142:143], off offset:400
	global_load_dwordx4 v[192:195], v[142:143], off offset:384
	global_load_dwordx4 v[196:199], v[170:171], off offset:384
	global_load_dwordx4 v[200:203], v[170:171], off offset:400
	s_waitcnt vmcnt(20)
	v_pk_fma_f32 v[48:49], v[32:33], v[216:217], v[220:221]
	v_pk_fma_f32 v[50:51], v[34:35], v[218:219], v[222:223]
	v_pk_fma_f32 v[52:53], v[40:41], v[212:213], v[224:225]
	v_pk_fma_f32 v[54:55], v[42:43], v[214:215], v[226:227]
	global_store_dwordx4 v[146:147], v[48:51], off offset:128
	global_store_dwordx4 v[146:147], v[52:55], off offset:144
	global_load_dwordx4 v[212:215], v[142:143], off offset:464
	global_load_dwordx4 v[216:219], v[142:143], off offset:448
	global_load_dwordx4 v[220:223], v[170:171], off offset:448
	global_load_dwordx4 v[224:227], v[170:171], off offset:464
	s_waitcnt vmcnt(22)
	v_pk_fma_f32 v[40:41], v[36:37], v[232:233], v[238:239]
	v_pk_fma_f32 v[44:45], v[44:45], v[228:229], v[242:243]
	v_pk_fma_f32 v[42:43], v[38:39], v[234:235], v[240:241]
	v_pk_fma_f32 v[46:47], v[46:47], v[230:231], v[244:245]
	global_store_dwordx4 v[146:147], v[40:43], off offset:192
	global_store_dwordx4 v[146:147], v[44:47], off offset:208
	s_waitcnt vmcnt(20)
	v_pk_fma_f32 v[32:33], v[16:17], v[250:251], v[162:163]
	v_pk_fma_f32 v[34:35], v[18:19], v[252:253], v[164:165]
	v_pk_fma_f32 v[36:37], v[24:25], v[246:247], v[166:167]
	v_pk_fma_f32 v[38:39], v[26:27], v[248:249], v[168:169]
	global_store_dwordx4 v[146:147], v[32:35], off offset:256
	global_store_dwordx4 v[146:147], v[36:39], off offset:272
	s_waitcnt vmcnt(16)
	v_pk_fma_f32 v[20:21], v[20:21], v[176:177], v[180:181]
	v_pk_fma_f32 v[24:25], v[28:29], v[172:173], v[184:185]
	v_pk_fma_f32 v[22:23], v[22:23], v[178:179], v[182:183]
	v_pk_fma_f32 v[26:27], v[30:31], v[174:175], v[186:187]
	global_store_dwordx4 v[146:147], v[20:23], off offset:320
	global_store_dwordx4 v[146:147], v[24:27], off offset:336
	s_waitcnt vmcnt(12)
	v_pk_fma_f32 v[16:17], v[0:1], v[192:193], v[196:197]
	v_pk_fma_f32 v[18:19], v[2:3], v[194:195], v[198:199]
	v_pk_fma_f32 v[8:9], v[8:9], v[188:189], v[200:201]
	v_pk_fma_f32 v[10:11], v[10:11], v[190:191], v[202:203]
	global_store_dwordx4 v[146:147], v[16:19], off offset:384
	global_store_dwordx4 v[146:147], v[8:11], off offset:400
	s_waitcnt vmcnt(8)
	v_pk_fma_f32 v[0:1], v[4:5], v[216:217], v[220:221]
	v_pk_fma_f32 v[4:5], v[12:13], v[212:213], v[224:225]
	v_pk_fma_f32 v[2:3], v[6:7], v[218:219], v[222:223]
	v_pk_fma_f32 v[6:7], v[14:15], v[214:215], v[226:227]
	global_store_dwordx4 v[146:147], v[0:3], off offset:448
	global_store_dwordx4 v[146:147], v[4:7], off offset:464
	v_pk_mul_f32 v[12:13], v[128:129], v[128:129]
	v_pk_mul_f32 v[14:15], v[130:131], v[130:131]
	v_add_f32_e32 v12, v12, v13
	v_add_f32_e32 v12, v14, v12
	v_pk_mul_f32 v[28:29], v[120:121], v[120:121]
	v_add_f32_e32 v12, v15, v12
	v_add_f32_e32 v12, v12, v28
	v_pk_mul_f32 v[30:31], v[122:123], v[122:123]
	v_add_f32_e32 v12, v29, v12
	v_add_f32_e32 v12, v30, v12
	v_pk_mul_f32 v[142:143], v[132:133], v[132:133]
	v_add_f32_e32 v12, v31, v12
	v_add_f32_e32 v12, v142, v12
	v_pk_mul_f32 v[146:147], v[134:135], v[134:135]
	v_add_f32_e32 v12, v143, v12
	v_add_f32_e32 v12, v146, v12
	v_pk_mul_f32 v[148:149], v[124:125], v[124:125]
	v_add_f32_e32 v12, v147, v12
	v_add_f32_e32 v12, v148, v12
	v_pk_mul_f32 v[162:163], v[126:127], v[126:127]
	v_add_f32_e32 v12, v149, v12
	v_add_f32_e32 v12, v162, v12
	v_pk_mul_f32 v[164:165], v[112:113], v[112:113]
	v_add_f32_e32 v12, v163, v12
	v_add_f32_e32 v12, v164, v12
	v_pk_mul_f32 v[166:167], v[114:115], v[114:115]
	v_add_f32_e32 v12, v165, v12
	v_add_f32_e32 v12, v166, v12
	v_pk_mul_f32 v[168:169], v[104:105], v[104:105]
	v_add_f32_e32 v12, v167, v12
	v_add_f32_e32 v12, v168, v12
	v_pk_mul_f32 v[170:171], v[106:107], v[106:107]
	v_add_f32_e32 v12, v169, v12
	v_add_f32_e32 v12, v170, v12
	v_pk_mul_f32 v[172:173], v[116:117], v[116:117]
	v_add_f32_e32 v12, v171, v12
	v_add_f32_e32 v12, v172, v12
	v_pk_mul_f32 v[174:175], v[118:119], v[118:119]
	v_add_f32_e32 v12, v173, v12
	v_add_f32_e32 v12, v174, v12
	v_pk_mul_f32 v[176:177], v[108:109], v[108:109]
	v_add_f32_e32 v12, v175, v12
	v_add_f32_e32 v12, v176, v12
	v_pk_mul_f32 v[178:179], v[110:111], v[110:111]
	v_add_f32_e32 v12, v177, v12
	v_add_f32_e32 v12, v178, v12
	v_pk_mul_f32 v[180:181], v[96:97], v[96:97]
	v_add_f32_e32 v12, v179, v12
	v_add_f32_e32 v12, v180, v12
	v_pk_mul_f32 v[182:183], v[98:99], v[98:99]
	v_add_f32_e32 v12, v181, v12
	v_add_f32_e32 v12, v182, v12
	v_pk_mul_f32 v[184:185], v[88:89], v[88:89]
	v_add_f32_e32 v12, v183, v12
	v_add_f32_e32 v12, v184, v12
	v_pk_mul_f32 v[186:187], v[90:91], v[90:91]
	v_add_f32_e32 v12, v185, v12
	v_add_f32_e32 v12, v186, v12
	v_pk_mul_f32 v[188:189], v[100:101], v[100:101]
	v_add_f32_e32 v12, v187, v12
	v_add_f32_e32 v12, v188, v12
	v_pk_mul_f32 v[190:191], v[102:103], v[102:103]
	v_add_f32_e32 v12, v189, v12
	v_add_f32_e32 v12, v190, v12
	v_pk_mul_f32 v[192:193], v[92:93], v[92:93]
	v_add_f32_e32 v12, v191, v12
	v_add_f32_e32 v12, v192, v12
	v_pk_mul_f32 v[194:195], v[94:95], v[94:95]
	v_add_f32_e32 v12, v193, v12
	v_add_f32_e32 v12, v194, v12
	v_pk_mul_f32 v[196:197], v[80:81], v[80:81]
	v_add_f32_e32 v12, v195, v12
	v_add_f32_e32 v12, v196, v12
	v_pk_mul_f32 v[198:199], v[82:83], v[82:83]
	v_add_f32_e32 v12, v197, v12
	v_add_f32_e32 v12, v198, v12
	v_pk_mul_f32 v[200:201], v[72:73], v[72:73]
	v_add_f32_e32 v12, v199, v12
	v_add_f32_e32 v12, v200, v12
	v_pk_mul_f32 v[202:203], v[74:75], v[74:75]
	v_add_f32_e32 v12, v201, v12
	v_add_f32_e32 v12, v202, v12
	v_pk_mul_f32 v[204:205], v[84:85], v[84:85]
	v_add_f32_e32 v12, v203, v12
	v_add_f32_e32 v12, v204, v12
	v_pk_mul_f32 v[206:207], v[86:87], v[86:87]
	v_add_f32_e32 v12, v205, v12
	v_add_f32_e32 v12, v206, v12
	v_pk_mul_f32 v[208:209], v[76:77], v[76:77]
	v_add_f32_e32 v12, v207, v12
	v_add_f32_e32 v12, v208, v12
	v_pk_mul_f32 v[210:211], v[78:79], v[78:79]
	v_add_f32_e32 v12, v209, v12
	v_add_f32_e32 v12, v210, v12
	v_add_f32_e32 v14, v211, v12
	ds_bpermute_b32 v15, v145, v14
	s_lshl_b64 s[56:57], s[82:83], 2
	s_add_u32 s56, s0, s56
	s_addc_u32 s57, s1, s57
	v_lshlrev_b32_e32 v12, 2, v152
	v_mov_b32_e32 v13, v137
	v_lshl_add_u64 v[12:13], s[56:57], 0, v[12:13]
	s_and_saveexec_b64 s[56:57], vcc
	s_cbranch_execz .LBB0_392
	s_waitcnt lgkmcnt(0)
	v_add_f32_e32 v14, v14, v15
	global_atomic_add_f32 v[12:13], v14, off

.LBB0_873:
	s_lshl_b32 s44, s50, 8
	s_add_i32 s44, s45, s44
	v_lshl_or_b32 v128, v134, 3, s2
	s_ashr_i32 s2, s44, 13
	v_or_b32_e32 v132, s46, v128
	s_mul_i32 s46, s2, 0xc00
	s_ashr_i32 s47, s46, 31
	s_lshl_b64 s[46:47], s[46:47], 2
	v_or_b32_e32 v138, s44, v148
	s_add_u32 s46, s28, s46
	v_ashrrev_i32_e32 v139, 31, v138
	v_readlane_b32 s64, v237, 1
	s_addc_u32 s47, s29, s47
	v_lshlrev_b64 v[128:129], 2, v[132:133]
	v_lshlrev_b64 v[134:135], 12, v[138:139]
	v_readlane_b32 s78, v237, 15
	v_readlane_b32 s79, v237, 16
	v_lshl_add_u64 v[130:131], s[46:47], 0, v[128:129]
	v_mov_b32 v136, 0
	v_lshl_add_u64 v[142:143], v[130:131], 0, s[42:43]
	v_lshl_add_u64 v[134:135], s[78:79], 0, v[134:135]
	v_lshl_add_u64 v[134:135], v[134:135], 0, v[128:129]
	v_add_co_u32_e32 v128, vcc, s59, v130
	v_readlane_b32 s65, v237, 2
	s_nop 0
	v_addc_co_u32_e32 v129, vcc, 0, v131, vcc
	global_load_dwordx4 v[208:211], v[128:129], off
	global_load_dwordx4 v[212:215], v[134:135], off offset:16
	global_load_dwordx4 v[216:219], v[134:135], off
	global_load_dwordx4 v[220:223], v[142:143], off offset:16
	global_load_dwordx4 v[224:227], v[142:143], off offset:80
	global_load_dwordx4 v[228:231], v[142:143], off offset:64
	global_load_dwordx4 v[232:235], v[134:135], off offset:64
	global_load_dwordx4 v[238:241], v[134:135], off offset:80
	global_load_dwordx4 v[242:245], v[142:143], off offset:144
	global_load_dwordx4 v[246:249], v[142:143], off offset:128
	global_load_dwordx4 v[250:253], v[134:135], off offset:128
	global_load_dwordx4 v[150:153], v[134:135], off offset:144
	global_load_dwordx4 v[156:159], v[142:143], off offset:208
	global_load_dwordx4 v[160:163], v[142:143], off offset:192
	global_load_dwordx4 v[164:167], v[134:135], off offset:192
	global_load_dwordx4 v[168:171], v[134:135], off offset:208
	global_load_dwordx4 v[172:175], v[142:143], off offset:272
	global_load_dwordx4 v[176:179], v[142:143], off offset:256
	global_load_dwordx4 v[180:183], v[134:135], off offset:256
	global_load_dwordx4 v[184:187], v[134:135], off offset:272
	global_load_dwordx4 v[188:191], v[142:143], off offset:336
	global_load_dwordx4 v[192:195], v[142:143], off offset:320
	global_load_dwordx4 v[196:199], v[134:135], off offset:320
	global_load_dwordx4 v[200:203], v[134:135], off offset:336
	v_cmp_ne_u32_e32 vcc, 0, v136
	v_readlane_b32 s66, v237, 3
	v_readlane_b32 s67, v237, 4
	v_readlane_b32 s68, v237, 5
	v_readlane_b32 s69, v237, 6
	v_readlane_b32 s70, v237, 7
	v_readlane_b32 s71, v237, 8
	v_readlane_b32 s72, v237, 9
	v_readlane_b32 s73, v237, 10
	v_readlane_b32 s74, v237, 11
	v_readlane_b32 s75, v237, 12
	v_readlane_b32 s76, v237, 13
	v_readlane_b32 s77, v237, 14
	s_waitcnt vmcnt(20)
	v_pk_fma_f32 v[128:129], v[112:113], v[208:209], v[216:217]
	v_pk_fma_f32 v[112:113], v[120:121], v[220:221], v[212:213]
	v_pk_fma_f32 v[130:131], v[114:115], v[210:211], v[218:219]
	v_pk_fma_f32 v[114:115], v[122:123], v[222:223], v[214:215]
	global_load_dwordx4 v[208:211], v[142:143], off offset:400
	global_load_dwordx4 v[212:215], v[142:143], off offset:384
	global_load_dwordx4 v[216:219], v[134:135], off offset:384
	global_load_dwordx4 v[220:223], v[134:135], off offset:400
	s_waitcnt vmcnt(20)
	v_pk_fma_f32 v[120:121], v[116:117], v[228:229], v[232:233]
	v_pk_fma_f32 v[116:117], v[124:125], v[224:225], v[238:239]
	v_pk_fma_f32 v[122:123], v[118:119], v[230:231], v[234:235]
	v_pk_fma_f32 v[118:119], v[126:127], v[226:227], v[240:241]
	global_load_dwordx4 v[224:227], v[142:143], off offset:464
	global_load_dwordx4 v[228:231], v[142:143], off offset:448
	global_load_dwordx4 v[232:235], v[134:135], off offset:448
	global_load_dwordx4 v[238:241], v[134:135], off offset:464
	s_waitcnt vmcnt(20)
	v_pk_fma_f32 v[124:125], v[96:97], v[246:247], v[250:251]
	v_pk_fma_f32 v[96:97], v[104:105], v[242:243], v[150:151]
	v_pk_fma_f32 v[126:127], v[98:99], v[248:249], v[252:253]
	v_pk_fma_f32 v[98:99], v[106:107], v[244:245], v[152:153]
	s_waitcnt vmcnt(16)
	v_pk_fma_f32 v[104:105], v[100:101], v[160:161], v[164:165]
	v_pk_fma_f32 v[100:101], v[108:109], v[156:157], v[168:169]
	v_pk_fma_f32 v[106:107], v[102:103], v[162:163], v[166:167]
	v_pk_fma_f32 v[102:103], v[110:111], v[158:159], v[170:171]
	s_waitcnt vmcnt(12)
	v_pk_fma_f32 v[108:109], v[80:81], v[176:177], v[180:181]
	v_pk_fma_f32 v[80:81], v[88:89], v[172:173], v[184:185]
	v_pk_fma_f32 v[110:111], v[82:83], v[178:179], v[182:183]
	v_pk_fma_f32 v[82:83], v[90:91], v[174:175], v[186:187]
	s_waitcnt vmcnt(8)
	v_pk_fma_f32 v[88:89], v[84:85], v[192:193], v[196:197]
	v_pk_fma_f32 v[84:85], v[92:93], v[188:189], v[200:201]
	v_pk_fma_f32 v[90:91], v[86:87], v[194:195], v[198:199]
	v_pk_fma_f32 v[86:87], v[94:95], v[190:191], v[202:203]
	s_waitcnt vmcnt(4)
	v_pk_fma_f32 v[92:93], v[64:65], v[212:213], v[216:217]
	v_pk_fma_f32 v[64:65], v[72:73], v[208:209], v[220:221]
	v_pk_fma_f32 v[94:95], v[66:67], v[214:215], v[218:219]
	v_pk_fma_f32 v[66:67], v[74:75], v[210:211], v[222:223]
	s_waitcnt vmcnt(0)
	v_pk_fma_f32 v[72:73], v[68:69], v[228:229], v[232:233]
	v_pk_fma_f32 v[68:69], v[76:77], v[224:225], v[238:239]
	v_pk_fma_f32 v[74:75], v[70:71], v[230:231], v[234:235]
	v_pk_fma_f32 v[70:71], v[78:79], v[226:227], v[240:241]
	v_or_b32_e32 v140, 32, v138
	v_ashrrev_i32_e32 v141, 31, v140
	v_readlane_b32 s64, v237, 1
	v_lshlrev_b64 v[76:77], 12, v[140:141]
	v_readlane_b32 s78, v237, 15
	v_readlane_b32 s79, v237, 16
	v_readlane_b32 s65, v237, 2
	v_readlane_b32 s66, v237, 3
	v_lshl_add_u64 v[76:77], s[78:79], 0, v[76:77]
	v_lshl_add_u64 v[136:137], v[132:133], 2, v[76:77]
	global_load_dwordx4 v[242:245], v[142:143], off offset:16
	global_load_dwordx4 v[246:249], v[142:143], off
	global_load_dwordx4 v[250:253], v[136:137], off
	global_load_dwordx4 v[150:153], v[136:137], off offset:16
	global_load_dwordx4 v[156:159], v[142:143], off offset:80
	global_load_dwordx4 v[160:163], v[142:143], off offset:64
	global_load_dwordx4 v[164:167], v[136:137], off offset:64
	global_load_dwordx4 v[168:171], v[136:137], off offset:80
	global_load_dwordx4 v[172:175], v[142:143], off offset:144
	global_load_dwordx4 v[176:179], v[142:143], off offset:128
	global_load_dwordx4 v[180:183], v[136:137], off offset:128
	global_load_dwordx4 v[184:187], v[136:137], off offset:144
	global_load_dwordx4 v[188:191], v[142:143], off offset:208
	global_load_dwordx4 v[192:195], v[142:143], off offset:192
	global_load_dwordx4 v[196:199], v[136:137], off offset:192
	global_load_dwordx4 v[200:203], v[136:137], off offset:208
	global_load_dwordx4 v[208:211], v[142:143], off offset:272
	global_load_dwordx4 v[212:215], v[142:143], off offset:256
	global_load_dwordx4 v[216:219], v[136:137], off offset:256
	global_load_dwordx4 v[220:223], v[136:137], off offset:272
	global_load_dwordx4 v[224:227], v[142:143], off offset:336
	global_load_dwordx4 v[228:231], v[142:143], off offset:320
	global_load_dwordx4 v[232:235], v[136:137], off offset:320
	global_load_dwordx4 v[238:241], v[136:137], off offset:336
	v_readlane_b32 s67, v237, 4
	v_readlane_b32 s68, v237, 5
	v_readlane_b32 s69, v237, 6
	v_readlane_b32 s70, v237, 7
	v_readlane_b32 s71, v237, 8
	v_readlane_b32 s72, v237, 9
	v_readlane_b32 s73, v237, 10
	v_readlane_b32 s74, v237, 11
	v_readlane_b32 s75, v237, 12
	v_readlane_b32 s76, v237, 13
	v_readlane_b32 s77, v237, 14
	s_waitcnt vmcnt(20)
	v_pk_fma_f32 v[76:77], v[48:49], v[246:247], v[250:251]
	v_pk_fma_f32 v[48:49], v[56:57], v[242:243], v[150:151]
	v_pk_fma_f32 v[78:79], v[50:51], v[248:249], v[252:253]
	v_pk_fma_f32 v[50:51], v[58:59], v[244:245], v[152:153]
	global_load_dwordx4 v[242:245], v[142:143], off offset:400
	global_load_dwordx4 v[246:249], v[142:143], off offset:384
	global_load_dwordx4 v[250:253], v[136:137], off offset:384
	global_load_dwordx4 v[150:153], v[136:137], off offset:400
	s_waitcnt vmcnt(20)
	v_pk_fma_f32 v[56:57], v[52:53], v[160:161], v[164:165]
	v_pk_fma_f32 v[52:53], v[60:61], v[156:157], v[168:169]
	v_pk_fma_f32 v[58:59], v[54:55], v[162:163], v[166:167]
	v_pk_fma_f32 v[54:55], v[62:63], v[158:159], v[170:171]
	global_load_dwordx4 v[156:159], v[142:143], off offset:464
	global_load_dwordx4 v[160:163], v[142:143], off offset:448
	global_load_dwordx4 v[164:167], v[136:137], off offset:448
	global_load_dwordx4 v[168:171], v[136:137], off offset:464
	s_waitcnt vmcnt(20)
	v_pk_fma_f32 v[60:61], v[32:33], v[176:177], v[180:181]
	v_pk_fma_f32 v[32:33], v[40:41], v[172:173], v[184:185]
	v_pk_fma_f32 v[62:63], v[34:35], v[178:179], v[182:183]
	v_pk_fma_f32 v[34:35], v[42:43], v[174:175], v[186:187]
	s_waitcnt vmcnt(16)
	v_pk_fma_f32 v[40:41], v[36:37], v[192:193], v[196:197]
	v_pk_fma_f32 v[36:37], v[44:45], v[188:189], v[200:201]
	v_pk_fma_f32 v[42:43], v[38:39], v[194:195], v[198:199]
	v_pk_fma_f32 v[38:39], v[46:47], v[190:191], v[202:203]
	s_waitcnt vmcnt(12)
	v_pk_fma_f32 v[44:45], v[16:17], v[212:213], v[216:217]
	v_pk_fma_f32 v[16:17], v[24:25], v[208:209], v[220:221]
	v_pk_fma_f32 v[46:47], v[18:19], v[214:215], v[218:219]
	v_pk_fma_f32 v[18:19], v[26:27], v[210:211], v[222:223]
	s_waitcnt vmcnt(8)
	v_pk_fma_f32 v[24:25], v[20:21], v[228:229], v[232:233]
	v_pk_fma_f32 v[20:21], v[28:29], v[224:225], v[238:239]
	v_pk_fma_f32 v[26:27], v[22:23], v[230:231], v[234:235]
	v_pk_fma_f32 v[22:23], v[30:31], v[226:227], v[240:241]
	s_waitcnt vmcnt(4)
	v_pk_fma_f32 v[28:29], v[0:1], v[246:247], v[250:251]
	v_pk_fma_f32 v[0:1], v[8:9], v[242:243], v[150:151]
	v_pk_fma_f32 v[30:31], v[2:3], v[248:249], v[252:253]
	v_pk_fma_f32 v[2:3], v[10:11], v[244:245], v[152:153]
	s_waitcnt vmcnt(0)
	v_pk_fma_f32 v[8:9], v[4:5], v[160:161], v[164:165]
	v_pk_fma_f32 v[4:5], v[12:13], v[156:157], v[168:169]
	v_pk_fma_f32 v[10:11], v[6:7], v[162:163], v[166:167]
	v_pk_fma_f32 v[6:7], v[14:15], v[158:159], v[170:171]
	s_ashr_i32 s45, s44, 31
	v_cmp_gt_u32_e32 vcc, 32, v149
	v_pk_mul_f32 v[12:13], v[128:129], v[128:129]
	v_pk_mul_f32 v[14:15], v[130:131], v[130:131]
	v_add_f32_e32 v12, v12, v13
	v_add_f32_e32 v12, v14, v12
	v_pk_mul_f32 v[142:143], v[120:121], v[120:121]
	v_add_f32_e32 v12, v15, v12
	v_add_f32_e32 v12, v12, v142
	v_pk_mul_f32 v[150:151], v[122:123], v[122:123]
	v_add_f32_e32 v12, v143, v12
	v_add_f32_e32 v12, v150, v12
	v_pk_mul_f32 v[152:153], v[112:113], v[112:113]
	v_add_f32_e32 v12, v151, v12
	v_add_f32_e32 v12, v152, v12
	v_pk_mul_f32 v[154:155], v[114:115], v[114:115]
	v_add_f32_e32 v12, v153, v12
	v_add_f32_e32 v12, v154, v12
	v_pk_mul_f32 v[156:157], v[116:117], v[116:117]
	v_add_f32_e32 v12, v155, v12
	v_add_f32_e32 v12, v156, v12
	v_pk_mul_f32 v[158:159], v[118:119], v[118:119]
	v_add_f32_e32 v12, v157, v12
	v_add_f32_e32 v12, v158, v12
	v_pk_mul_f32 v[160:161], v[124:125], v[124:125]
	v_add_f32_e32 v12, v159, v12
	v_add_f32_e32 v12, v12, v160
	v_pk_mul_f32 v[162:163], v[126:127], v[126:127]
	v_add_f32_e32 v12, v161, v12
	v_add_f32_e32 v12, v162, v12
	v_pk_mul_f32 v[164:165], v[104:105], v[104:105]
	v_add_f32_e32 v12, v163, v12
	v_add_f32_e32 v12, v12, v164
	v_pk_mul_f32 v[166:167], v[106:107], v[106:107]
	v_add_f32_e32 v12, v165, v12
	v_add_f32_e32 v12, v166, v12
	v_pk_mul_f32 v[168:169], v[96:97], v[96:97]
	v_add_f32_e32 v12, v167, v12
	v_add_f32_e32 v12, v168, v12
	v_pk_mul_f32 v[170:171], v[98:99], v[98:99]
	v_add_f32_e32 v12, v169, v12
	v_add_f32_e32 v12, v170, v12
	v_pk_mul_f32 v[172:173], v[100:101], v[100:101]
	v_add_f32_e32 v12, v171, v12
	v_add_f32_e32 v12, v172, v12
	v_pk_mul_f32 v[174:175], v[102:103], v[102:103]
	v_add_f32_e32 v12, v173, v12
	v_add_f32_e32 v12, v174, v12
	v_pk_mul_f32 v[176:177], v[108:109], v[108:109]
	v_add_f32_e32 v12, v175, v12
	v_add_f32_e32 v12, v12, v176
	v_pk_mul_f32 v[178:179], v[110:111], v[110:111]
	v_add_f32_e32 v12, v177, v12
	v_add_f32_e32 v12, v178, v12
	v_pk_mul_f32 v[180:181], v[88:89], v[88:89]
	v_add_f32_e32 v12, v179, v12
	v_add_f32_e32 v12, v12, v180
	v_pk_mul_f32 v[182:183], v[90:91], v[90:91]
	v_add_f32_e32 v12, v181, v12
	v_add_f32_e32 v12, v182, v12
	v_pk_mul_f32 v[184:185], v[80:81], v[80:81]
	v_add_f32_e32 v12, v183, v12
	v_add_f32_e32 v12, v184, v12
	v_pk_mul_f32 v[186:187], v[82:83], v[82:83]
	v_add_f32_e32 v12, v185, v12
	v_add_f32_e32 v12, v186, v12
	v_pk_mul_f32 v[188:189], v[84:85], v[84:85]
	v_add_f32_e32 v12, v187, v12
	v_add_f32_e32 v12, v188, v12
	v_pk_mul_f32 v[190:191], v[86:87], v[86:87]
	v_add_f32_e32 v12, v189, v12
	v_add_f32_e32 v12, v190, v12
	v_pk_mul_f32 v[192:193], v[92:93], v[92:93]
	v_add_f32_e32 v12, v191, v12
	v_add_f32_e32 v12, v12, v192
	v_pk_mul_f32 v[194:195], v[94:95], v[94:95]
	v_add_f32_e32 v12, v193, v12
	v_add_f32_e32 v12, v194, v12
	v_pk_mul_f32 v[196:197], v[72:73], v[72:73]
	v_add_f32_e32 v12, v195, v12
	v_add_f32_e32 v12, v12, v196
	v_pk_mul_f32 v[198:199], v[74:75], v[74:75]
	v_add_f32_e32 v12, v197, v12
	v_add_f32_e32 v12, v198, v12
	v_pk_mul_f32 v[200:201], v[64:65], v[64:65]
	v_add_f32_e32 v12, v199, v12
	v_add_f32_e32 v12, v200, v12
	v_pk_mul_f32 v[202:203], v[66:67], v[66:67]
	v_add_f32_e32 v12, v201, v12
	v_add_f32_e32 v12, v202, v12
	v_pk_mul_f32 v[204:205], v[68:69], v[68:69]
	v_add_f32_e32 v12, v203, v12
	v_add_f32_e32 v12, v204, v12
	v_pk_mul_f32 v[206:207], v[70:71], v[70:71]
	v_add_f32_e32 v12, v205, v12
	v_add_f32_e32 v12, v206, v12
	v_add_f32_e32 v14, v207, v12
	ds_bpermute_b32 v15, v145, v14
	s_lshl_b64 s[44:45], s[44:45], 2
	s_add_u32 s44, s0, s44
	s_addc_u32 s45, s1, s45
	v_lshlrev_b32_e32 v12, 2, v148
	v_mov_b32_e32 v13, v133
	v_lshl_add_u64 v[12:13], s[44:45], 0, v[12:13]
	s_and_saveexec_b64 s[44:45], vcc
	s_cbranch_execz .LBB0_907
	s_waitcnt lgkmcnt(0)
	v_add_f32_e32 v14, v14, v15
	global_atomic_add_f32 v[12:13], v14, off
